# GU GEMM K-loop: last three LDS-DMA loads of each DMA-heavy load segment moved into the following MFMA segment (vmcnt 8->5, same coverage)
# baseline (speedup 1.0000x reference)
; #define PG8_STAGE(bufoff, gbase, voff) do { _Pragma("unroll") for (int _i = 0; _i < 2; ++_i) \
;         __builtin_amdgcn_global_load_lds((const unsigned*)((const char*)(gbase) + (voff)[_i]), (LAS unsigned*)(lds + (bufoff) + ldsw + _i * 8192), 16, 0, 0); } while (0)
; #define PG8_LDA(dst, b, h) do { _Pragma("unroll") for (int m = 0; m < 4; ++m) _Pragma("unroll") for (int k = 0; k < 2; ++k) dst[m][k] = *(const LAS bf16x8*)(lds + PG8_SA(b, h) + aoff + m * 2048 + k * 1024); } while (0)
; #define PG8_LDB(dst, b, h) do { _Pragma("unroll") for (int n = 0; n < 2; ++n) _Pragma("unroll") for (int k = 0; k < 2; ++k) dst[n][k] = *(const LAS bf16x8*)(lds + PG8_SB(b, h) + boff + n * 2048 + k * 1024); } while (0)
; #define PG8_MMA(ai, bj, At, Bt) do { __builtin_amdgcn_s_setprio(1); _Pragma("unroll") for (int m = 0; m < 4; ++m) _Pragma("unroll") for (int n = 0; n < 2; ++n) _Pragma("unroll") for (int k = 0; k < 2; ++k) \
;         acc[ai][bj][m][n] = __builtin_amdgcn_mfma_f32_16x16x32_bf16(Bt[n][k], At[m][k], acc[ai][bj][m][n], 0, 0, 0); __builtin_amdgcn_s_setprio(0); } while (0)
; #define PG8_WAIT_V(n) asm volatile("s_waitcnt vmcnt(" #n ")" ::: "memory")
; #define PG8_WAIT_L(n) asm volatile("s_waitcnt lgkmcnt(" #n ")" ::: "memory")
; #define PG8_BAR __builtin_amdgcn_s_barrier()
; #define PG8_SCHED __builtin_amdgcn_sched_barrier(0)
; template <class Epi, class Sched, bool ALIGN_EPI>
; DI void gemm_phase(LAS unsigned char* lds, const Gemm g, const Sched& Sc, const Epi& E, const int tid) {
;     ...
;             PG8_LDB(B0, 0, 0); PG8_LDB(B1, 0, 1); PG8_SCHED; PG8_LDA(At, 0, 0); PG8_STAGE(PG8_SA(1, 1), a1 + hA, voffA);
;             PG8_WAIT_V(8); PG8_WAIT_L(0); PG8_BAR; PG8_MMA(0, 0, At, B0); PG8_MMA(0, 1, At, B1); PG8_BAR; PG8_SCHED;
;             PG8_LDA(At, 0, 1); PG8_STAGE(PG8_SB(0, 0), b2, voffB); PG8_STAGE(PG8_SB(0, 1), b2 + hB, voffB); PG8_STAGE(PG8_SA(0, 0), a2, voffA);
;             PG8_WAIT_V(8); PG8_WAIT_L(0); PG8_BAR; PG8_MMA(1, 0, At, B0); PG8_MMA(1, 1, At, B1); PG8_BAR; PG8_SCHED;
.LBB0_2634:
	v_add_u32_e32 v147, s39, v143
	ds_read_b128 v[148:151], v147
	ds_read_b128 v[152:155], v147 offset:1024
	ds_read_b128 v[156:159], v147 offset:2048
	ds_read_b128 v[160:163], v147 offset:3072
	v_add_u32_e32 v147, s48, v143
	ds_read_b128 v[164:167], v147
	ds_read_b128 v[168:171], v147 offset:1024
	ds_read_b128 v[172:175], v147 offset:2048
	ds_read_b128 v[176:179], v147 offset:3072
	s_add_u32 s42, s40, 0xfff80080
	s_addc_u32 s43, s41, -1
	s_cmp_eq_u32 s75, 28
	s_cselect_b32 s45, s23, s43
	s_cselect_b32 s44, s71, s42
	s_cselect_b32 s43, s19, s74
	s_cselect_b32 s42, s72, s73
	v_lshl_add_u64 v[222:223], s[40:41], 0, v[140:141]
	s_add_i32 m0, s51, 0xc000
	ds_read_b128 v[180:183], v146
	ds_read_b128 v[184:187], v146 offset:1024
	ds_read_b128 v[188:191], v146 offset:2048
	ds_read_b128 v[192:195], v146 offset:3072
	ds_read_b128 v[198:201], v146 offset:4096
	ds_read_b128 v[210:213], v146 offset:5120
	ds_read_b128 v[214:217], v146 offset:6144
	ds_read_b128 v[218:221], v146 offset:7168
	global_load_lds_dwordx4 v[222:223], off
	v_lshl_add_u64 v[222:223], s[40:41], 0, v[138:139]
	s_add_i32 m0, s51, 0xe000
	s_nop 0
	global_load_lds_dwordx4 v[222:223], off
	s_waitcnt vmcnt(8)
	s_waitcnt lgkmcnt(0)
	s_barrier
	s_setprio 1
	s_waitcnt lgkmcnt(0)
	v_mfma_f32_16x16x32_bf16 v[128:131], v[148:151], v[180:183], v[128:131]
	v_mfma_f32_16x16x32_bf16 v[124:127], v[156:159], v[180:183], v[124:127]
	v_mfma_f32_16x16x32_bf16 v[120:123], v[148:151], v[188:191], v[120:123]
	v_mfma_f32_16x16x32_bf16 v[116:119], v[156:159], v[188:191], v[116:119]
	v_mfma_f32_16x16x32_bf16 v[104:107], v[148:151], v[198:201], v[104:107]
	v_mfma_f32_16x16x32_bf16 v[100:103], v[156:159], v[198:201], v[100:103]
	v_mfma_f32_16x16x32_bf16 v[88:91], v[148:151], v[214:217], v[88:91]
	v_mfma_f32_16x16x32_bf16 v[84:87], v[156:159], v[214:217], v[84:87]
	v_mfma_f32_16x16x32_bf16 v[128:131], v[152:155], v[184:187], v[128:131]
	v_mfma_f32_16x16x32_bf16 v[124:127], v[160:163], v[184:187], v[124:127]
	v_mfma_f32_16x16x32_bf16 v[120:123], v[152:155], v[192:195], v[120:123]
	v_mfma_f32_16x16x32_bf16 v[116:119], v[160:163], v[192:195], v[116:119]
	v_mfma_f32_16x16x32_bf16 v[104:107], v[152:155], v[210:213], v[104:107]
	v_mfma_f32_16x16x32_bf16 v[100:103], v[160:163], v[210:213], v[100:103]
	v_mfma_f32_16x16x32_bf16 v[88:91], v[152:155], v[218:221], v[88:91]
	v_mfma_f32_16x16x32_bf16 v[84:87], v[160:163], v[218:221], v[84:87]
	s_setprio 0
	s_setprio 1
	v_mfma_f32_16x16x32_bf16 v[112:115], v[164:167], v[180:183], v[112:115]
	v_mfma_f32_16x16x32_bf16 v[108:111], v[172:175], v[180:183], v[108:111]
	v_mfma_f32_16x16x32_bf16 v[96:99], v[164:167], v[188:191], v[96:99]
	v_mfma_f32_16x16x32_bf16 v[92:95], v[172:175], v[188:191], v[92:95]
	v_mfma_f32_16x16x32_bf16 v[80:83], v[164:167], v[198:201], v[80:83]
	v_mfma_f32_16x16x32_bf16 v[76:79], v[172:175], v[198:201], v[76:79]
	v_mfma_f32_16x16x32_bf16 v[72:75], v[164:167], v[214:217], v[72:75]
	v_mfma_f32_16x16x32_bf16 v[68:71], v[172:175], v[214:217], v[68:71]
	v_mfma_f32_16x16x32_bf16 v[112:115], v[168:171], v[184:187], v[112:115]
	v_mfma_f32_16x16x32_bf16 v[108:111], v[176:179], v[184:187], v[108:111]
	v_mfma_f32_16x16x32_bf16 v[96:99], v[168:171], v[192:195], v[96:99]
	v_mfma_f32_16x16x32_bf16 v[92:95], v[176:179], v[192:195], v[92:95]
	v_mfma_f32_16x16x32_bf16 v[80:83], v[168:171], v[210:213], v[80:83]
	v_mfma_f32_16x16x32_bf16 v[76:79], v[176:179], v[210:213], v[76:79]
	v_mfma_f32_16x16x32_bf16 v[72:75], v[168:171], v[218:221], v[72:75]
	v_mfma_f32_16x16x32_bf16 v[68:71], v[176:179], v[218:221], v[68:71]
	s_setprio 0
	s_barrier
	s_mov_b32 m0, s46
	v_lshl_add_u64 v[222:223], s[42:43], 0, v[18:19]
	s_add_u32 s76, s42, 0x80000
	ds_read_b128 v[180:183], v146 offset:16384
	ds_read_b128 v[184:187], v146 offset:17408
	ds_read_b128 v[188:191], v146 offset:18432
	ds_read_b128 v[192:195], v146 offset:19456
	ds_read_b128 v[198:201], v146 offset:20480
	ds_read_b128 v[210:213], v146 offset:21504
	ds_read_b128 v[214:217], v146 offset:22528
	ds_read_b128 v[218:221], v146 offset:23552
	global_load_lds_dwordx4 v[222:223], off
	v_lshl_add_u64 v[224:225], s[42:43], 0, v[132:133]
	s_mov_b32 m0, s47
	s_addc_u32 s77, s43, 0
	global_load_lds_dwordx4 v[224:225], off
	v_lshl_add_u64 v[226:227], s[76:77], 0, v[18:19]
	s_mov_b32 m0, s49
	v_lshl_add_u64 v[228:229], s[44:45], 0, v[134:135]
	global_load_lds_dwordx4 v[226:227], off
	s_waitcnt vmcnt(5)
	s_waitcnt lgkmcnt(0)
	s_barrier
; #define PG8_STAGE(bufoff, gbase, voff) do { _Pragma("unroll") for (int _i = 0; _i < 2; ++_i) \
;         __builtin_amdgcn_global_load_lds((const unsigned*)((const char*)(gbase) + (voff)[_i]), (LAS unsigned*)(lds + (bufoff) + ldsw + _i * 8192), 16, 0, 0); } while (0)
; #define PG8_LDA(dst, b, h) do { _Pragma("unroll") for (int m = 0; m < 4; ++m) _Pragma("unroll") for (int k = 0; k < 2; ++k) dst[m][k] = *(const LAS bf16x8*)(lds + PG8_SA(b, h) + aoff + m * 2048 + k * 1024); } while (0)
; #define PG8_LDB(dst, b, h) do { _Pragma("unroll") for (int n = 0; n < 2; ++n) _Pragma("unroll") for (int k = 0; k < 2; ++k) dst[n][k] = *(const LAS bf16x8*)(lds + PG8_SB(b, h) + boff + n * 2048 + k * 1024); } while (0)
; #define PG8_MMA(ai, bj, At, Bt) do { __builtin_amdgcn_s_setprio(1); _Pragma("unroll") for (int m = 0; m < 4; ++m) _Pragma("unroll") for (int n = 0; n < 2; ++n) _Pragma("unroll") for (int k = 0; k < 2; ++k) \
;         acc[ai][bj][m][n] = __builtin_amdgcn_mfma_f32_16x16x32_bf16(Bt[n][k], At[m][k], acc[ai][bj][m][n], 0, 0, 0); __builtin_amdgcn_s_setprio(0); } while (0)
; #define PG8_WAIT_V(n) asm volatile("s_waitcnt vmcnt(" #n ")" ::: "memory")
; #define PG8_WAIT_L(n) asm volatile("s_waitcnt lgkmcnt(" #n ")" ::: "memory")
; #define PG8_BAR __builtin_amdgcn_s_barrier()
; #define PG8_SCHED __builtin_amdgcn_sched_barrier(0)
; template <class Epi, class Sched, bool ALIGN_EPI>
; DI void gemm_phase(LAS unsigned char* lds, const Gemm g, const Sched& Sc, const Epi& E, const int tid) {
;     ...
;             PG8_WAIT_V(8); PG8_WAIT_L(0); PG8_BAR; PG8_MMA(1, 0, At, B0); PG8_MMA(1, 1, At, B1); PG8_BAR; PG8_SCHED;
;             PG8_LDB(B0, 1, 0); PG8_LDB(B1, 1, 1); PG8_SCHED; PG8_LDA(At, 1, 0); PG8_STAGE(PG8_SA(0, 1), a2 + hA, voffA);
;             PG8_WAIT_V(8); PG8_WAIT_L(0); PG8_BAR; PG8_MMA(0, 0, At, B0); PG8_MMA(0, 1, At, B1); PG8_BAR; PG8_SCHED;
	s_setprio 1
	s_waitcnt lgkmcnt(0)
	v_mfma_f32_16x16x32_bf16 v[64:67], v[148:151], v[180:183], v[64:67]
	v_mfma_f32_16x16x32_bf16 v[60:63], v[156:159], v[180:183], v[60:63]
	v_mfma_f32_16x16x32_bf16 v[56:59], v[148:151], v[188:191], v[56:59]
	v_mfma_f32_16x16x32_bf16 v[52:55], v[156:159], v[188:191], v[52:55]
	v_mfma_f32_16x16x32_bf16 v[40:43], v[148:151], v[198:201], v[40:43]
	v_mfma_f32_16x16x32_bf16 v[36:39], v[156:159], v[198:201], v[36:39]
	v_mfma_f32_16x16x32_bf16 v[24:27], v[148:151], v[214:217], v[24:27]
	v_mfma_f32_16x16x32_bf16 v[20:23], v[156:159], v[214:217], v[20:23]
	v_lshl_add_u64 v[226:227], s[76:77], 0, v[132:133]
	s_mov_b32 m0, s50
	s_nop 0
	global_load_lds_dwordx4 v[226:227], off
	v_mfma_f32_16x16x32_bf16 v[64:67], v[152:155], v[184:187], v[64:67]
	v_mfma_f32_16x16x32_bf16 v[60:63], v[160:163], v[184:187], v[60:63]
	v_mfma_f32_16x16x32_bf16 v[56:59], v[152:155], v[192:195], v[56:59]
	v_mfma_f32_16x16x32_bf16 v[52:55], v[160:163], v[192:195], v[52:55]
	v_mfma_f32_16x16x32_bf16 v[40:43], v[152:155], v[210:213], v[40:43]
	v_mfma_f32_16x16x32_bf16 v[36:39], v[160:163], v[210:213], v[36:39]
	v_mfma_f32_16x16x32_bf16 v[24:27], v[152:155], v[218:221], v[24:27]
	v_mfma_f32_16x16x32_bf16 v[20:23], v[160:163], v[218:221], v[20:23]
	v_lshl_add_u64 v[226:227], s[44:45], 0, v[136:137]
	s_mov_b32 m0, s51
	s_nop 0
	global_load_lds_dwordx4 v[226:227], off
	s_setprio 0
	s_setprio 1
	v_mfma_f32_16x16x32_bf16 v[48:51], v[164:167], v[180:183], v[48:51]
	v_mfma_f32_16x16x32_bf16 v[44:47], v[172:175], v[180:183], v[44:47]
	v_mfma_f32_16x16x32_bf16 v[32:35], v[164:167], v[188:191], v[32:35]
	v_mfma_f32_16x16x32_bf16 v[28:31], v[172:175], v[188:191], v[28:31]
	v_mfma_f32_16x16x32_bf16 v[14:17], v[164:167], v[198:201], v[14:17]
	v_mfma_f32_16x16x32_bf16 v[10:13], v[172:175], v[198:201], v[10:13]
	v_mfma_f32_16x16x32_bf16 v[6:9], v[164:167], v[214:217], v[6:9]
	v_mfma_f32_16x16x32_bf16 v[2:5], v[172:175], v[214:217], v[2:5]
	s_mov_b32 m0, s52
	s_nop 0
	global_load_lds_dwordx4 v[228:229], off
	v_mfma_f32_16x16x32_bf16 v[48:51], v[168:171], v[184:187], v[48:51]
	v_mfma_f32_16x16x32_bf16 v[44:47], v[176:179], v[184:187], v[44:47]
	v_mfma_f32_16x16x32_bf16 v[32:35], v[168:171], v[192:195], v[32:35]
	v_mfma_f32_16x16x32_bf16 v[28:31], v[176:179], v[192:195], v[28:31]
	v_mfma_f32_16x16x32_bf16 v[14:17], v[168:171], v[210:213], v[14:17]
	v_mfma_f32_16x16x32_bf16 v[10:13], v[176:179], v[210:213], v[10:13]
	v_mfma_f32_16x16x32_bf16 v[6:9], v[168:171], v[218:221], v[6:9]
	v_mfma_f32_16x16x32_bf16 v[2:5], v[176:179], v[218:221], v[2:5]
	s_setprio 0
	s_barrier
	v_add_u32_e32 v147, s55, v143
	ds_read_b128 v[148:151], v147
	ds_read_b128 v[152:155], v147 offset:1024
	ds_read_b128 v[156:159], v147 offset:2048
	ds_read_b128 v[160:163], v147 offset:3072
	v_add_u32_e32 v147, s64, v143
	ds_read_b128 v[164:167], v147
	ds_read_b128 v[168:171], v147 offset:1024
	ds_read_b128 v[172:175], v147 offset:2048
	ds_read_b128 v[176:179], v147 offset:3072
	s_add_u32 s44, s44, 0x80000
	s_addc_u32 s45, s45, 0
	s_mov_b32 m0, s53
	v_lshl_add_u64 v[230:231], s[44:45], 0, v[136:137]
	ds_read_b128 v[180:183], v146 offset:32768
	ds_read_b128 v[184:187], v146 offset:33792
	ds_read_b128 v[188:191], v146 offset:34816
	ds_read_b128 v[192:195], v146 offset:35840
	ds_read_b128 v[198:201], v146 offset:36864
	ds_read_b128 v[210:213], v146 offset:37888
	ds_read_b128 v[214:217], v146 offset:38912
	ds_read_b128 v[218:221], v146 offset:39936
	global_load_lds_dwordx4 v[230:231], off
	v_lshl_add_u64 v[230:231], s[44:45], 0, v[134:135]
	s_mov_b32 m0, s54
	s_nop 0
	global_load_lds_dwordx4 v[230:231], off
	s_waitcnt vmcnt(8)
	s_waitcnt lgkmcnt(0)
	s_barrier
	s_setprio 1
	s_waitcnt lgkmcnt(0)
	v_mfma_f32_16x16x32_bf16 v[128:131], v[148:151], v[180:183], v[128:131]
	v_mfma_f32_16x16x32_bf16 v[124:127], v[156:159], v[180:183], v[124:127]
	v_mfma_f32_16x16x32_bf16 v[120:123], v[148:151], v[188:191], v[120:123]
	v_mfma_f32_16x16x32_bf16 v[116:119], v[156:159], v[188:191], v[116:119]
	v_mfma_f32_16x16x32_bf16 v[104:107], v[148:151], v[198:201], v[104:107]
	v_mfma_f32_16x16x32_bf16 v[100:103], v[156:159], v[198:201], v[100:103]
	v_mfma_f32_16x16x32_bf16 v[88:91], v[148:151], v[214:217], v[88:91]
	v_mfma_f32_16x16x32_bf16 v[84:87], v[156:159], v[214:217], v[84:87]
	v_mfma_f32_16x16x32_bf16 v[128:131], v[152:155], v[184:187], v[128:131]
	v_mfma_f32_16x16x32_bf16 v[124:127], v[160:163], v[184:187], v[124:127]
	v_mfma_f32_16x16x32_bf16 v[120:123], v[152:155], v[192:195], v[120:123]
	v_mfma_f32_16x16x32_bf16 v[116:119], v[160:163], v[192:195], v[116:119]
	v_mfma_f32_16x16x32_bf16 v[104:107], v[152:155], v[210:213], v[104:107]
	v_mfma_f32_16x16x32_bf16 v[100:103], v[160:163], v[210:213], v[100:103]
	v_mfma_f32_16x16x32_bf16 v[88:91], v[152:155], v[218:221], v[88:91]
	v_mfma_f32_16x16x32_bf16 v[84:87], v[160:163], v[218:221], v[84:87]
	s_setprio 0
	s_setprio 1
	v_mfma_f32_16x16x32_bf16 v[112:115], v[164:167], v[180:183], v[112:115]
	v_mfma_f32_16x16x32_bf16 v[108:111], v[172:175], v[180:183], v[108:111]
	v_mfma_f32_16x16x32_bf16 v[96:99], v[164:167], v[188:191], v[96:99]
	v_mfma_f32_16x16x32_bf16 v[92:95], v[172:175], v[188:191], v[92:95]
	v_mfma_f32_16x16x32_bf16 v[80:83], v[164:167], v[198:201], v[80:83]
	v_mfma_f32_16x16x32_bf16 v[76:79], v[172:175], v[198:201], v[76:79]
	v_mfma_f32_16x16x32_bf16 v[72:75], v[164:167], v[214:217], v[72:75]
	v_mfma_f32_16x16x32_bf16 v[68:71], v[172:175], v[214:217], v[68:71]
	v_mfma_f32_16x16x32_bf16 v[112:115], v[168:171], v[184:187], v[112:115]
	v_mfma_f32_16x16x32_bf16 v[108:111], v[176:179], v[184:187], v[108:111]
	v_mfma_f32_16x16x32_bf16 v[96:99], v[168:171], v[192:195], v[96:99]
	v_mfma_f32_16x16x32_bf16 v[92:95], v[176:179], v[192:195], v[92:95]
	v_mfma_f32_16x16x32_bf16 v[80:83], v[168:171], v[210:213], v[80:83]
	v_mfma_f32_16x16x32_bf16 v[76:79], v[176:179], v[210:213], v[76:79]
	v_mfma_f32_16x16x32_bf16 v[72:75], v[168:171], v[218:221], v[72:75]
	v_mfma_f32_16x16x32_bf16 v[68:71], v[176:179], v[218:221], v[68:71]
	s_setprio 0
	s_barrier
; #define PG8_STAGE(bufoff, gbase, voff) do { _Pragma("unroll") for (int _i = 0; _i < 2; ++_i) \
;         __builtin_amdgcn_global_load_lds((const unsigned*)((const char*)(gbase) + (voff)[_i]), (LAS unsigned*)(lds + (bufoff) + ldsw + _i * 8192), 16, 0, 0); } while (0)
; #define PG8_LDA(dst, b, h) do { _Pragma("unroll") for (int m = 0; m < 4; ++m) _Pragma("unroll") for (int k = 0; k < 2; ++k) dst[m][k] = *(const LAS bf16x8*)(lds + PG8_SA(b, h) + aoff + m * 2048 + k * 1024); } while (0)
; #define PG8_MMA(ai, bj, At, Bt) do { __builtin_amdgcn_s_setprio(1); _Pragma("unroll") for (int m = 0; m < 4; ++m) _Pragma("unroll") for (int n = 0; n < 2; ++n) _Pragma("unroll") for (int k = 0; k < 2; ++k) \
;         acc[ai][bj][m][n] = __builtin_amdgcn_mfma_f32_16x16x32_bf16(Bt[n][k], At[m][k], acc[ai][bj][m][n], 0, 0, 0); __builtin_amdgcn_s_setprio(0); } while (0)
; #define PG8_WAIT_V(n) asm volatile("s_waitcnt vmcnt(" #n ")" ::: "memory")
; #define PG8_WAIT_L(n) asm volatile("s_waitcnt lgkmcnt(" #n ")" ::: "memory")
; #define PG8_BAR __builtin_amdgcn_s_barrier()
; #define PG8_SCHED __builtin_amdgcn_sched_barrier(0)
; template <class Epi, class Sched, bool ALIGN_EPI>
; DI void gemm_phase(LAS unsigned char* lds, const Gemm g, const Sched& Sc, const Epi& E, const int tid) {
;     ...
;             PG8_LDA(At, 1, 1); PG8_STAGE(PG8_SB(1, 0), b3, voffB); PG8_STAGE(PG8_SB(1, 1), b3 + hB, voffB); PG8_STAGE(PG8_SA(1, 0), a3, voffA);
;             PG8_WAIT_V(8); PG8_WAIT_L(0); PG8_BAR; PG8_MMA(1, 0, At, B0); PG8_MMA(1, 1, At, B1); PG8_BAR; PG8_SCHED;
;         }
;         if constexpr (ALIGN_EPI) { if (wr == 0) PG8_BAR; }
	s_mov_b32 m0, s56
	v_lshl_add_u64 v[222:223], v[222:223], 0, s[60:61]
	s_add_u32 s42, s42, 0x80080
	ds_read_b128 v[180:183], v146 offset:49152
	ds_read_b128 v[184:187], v146 offset:50176
	ds_read_b128 v[188:191], v146 offset:51200
	ds_read_b128 v[192:195], v146 offset:52224
	ds_read_b128 v[198:201], v146 offset:53248
	ds_read_b128 v[210:213], v146 offset:54272
	ds_read_b128 v[214:217], v146 offset:55296
	ds_read_b128 v[218:221], v146 offset:56320
	global_load_lds_dwordx4 v[222:223], off
	v_lshl_add_u64 v[222:223], v[224:225], 0, s[60:61]
	s_mov_b32 m0, s57
	s_addc_u32 s43, s43, 0
	global_load_lds_dwordx4 v[222:223], off
	v_lshl_add_u64 v[222:223], s[42:43], 0, v[18:19]
	s_mov_b32 m0, s65
	s_nop 0
	global_load_lds_dwordx4 v[222:223], off
	s_waitcnt vmcnt(5)
	s_waitcnt lgkmcnt(0)
	s_barrier
	s_setprio 1
	s_waitcnt lgkmcnt(0)
	v_mfma_f32_16x16x32_bf16 v[64:67], v[148:151], v[180:183], v[64:67]
	v_mfma_f32_16x16x32_bf16 v[60:63], v[156:159], v[180:183], v[60:63]
	v_mfma_f32_16x16x32_bf16 v[56:59], v[148:151], v[188:191], v[56:59]
	v_mfma_f32_16x16x32_bf16 v[52:55], v[156:159], v[188:191], v[52:55]
	v_mfma_f32_16x16x32_bf16 v[40:43], v[148:151], v[198:201], v[40:43]
	v_mfma_f32_16x16x32_bf16 v[36:39], v[156:159], v[198:201], v[36:39]
	v_mfma_f32_16x16x32_bf16 v[24:27], v[148:151], v[214:217], v[24:27]
	v_mfma_f32_16x16x32_bf16 v[20:23], v[156:159], v[214:217], v[20:23]
	v_lshl_add_u64 v[222:223], s[42:43], 0, v[132:133]
	s_mov_b32 m0, s66
	s_nop 0
	global_load_lds_dwordx4 v[222:223], off
	v_mfma_f32_16x16x32_bf16 v[64:67], v[152:155], v[184:187], v[64:67]
	v_mfma_f32_16x16x32_bf16 v[60:63], v[160:163], v[184:187], v[60:63]
	v_mfma_f32_16x16x32_bf16 v[56:59], v[152:155], v[192:195], v[56:59]
	v_mfma_f32_16x16x32_bf16 v[52:55], v[160:163], v[192:195], v[52:55]
	v_mfma_f32_16x16x32_bf16 v[40:43], v[152:155], v[210:213], v[40:43]
	v_mfma_f32_16x16x32_bf16 v[36:39], v[160:163], v[210:213], v[36:39]
	v_mfma_f32_16x16x32_bf16 v[24:27], v[152:155], v[218:221], v[24:27]
	v_mfma_f32_16x16x32_bf16 v[20:23], v[160:163], v[218:221], v[20:23]
	v_lshl_add_u64 v[222:223], v[226:227], 0, s[60:61]
	s_mov_b32 m0, s62
	s_nop 0
	global_load_lds_dwordx4 v[222:223], off
	s_setprio 0
	s_setprio 1
	v_mfma_f32_16x16x32_bf16 v[48:51], v[164:167], v[180:183], v[48:51]
	v_mfma_f32_16x16x32_bf16 v[44:47], v[172:175], v[180:183], v[44:47]
	v_mfma_f32_16x16x32_bf16 v[32:35], v[164:167], v[188:191], v[32:35]
	v_mfma_f32_16x16x32_bf16 v[28:31], v[172:175], v[188:191], v[28:31]
	v_mfma_f32_16x16x32_bf16 v[14:17], v[164:167], v[198:201], v[14:17]
	v_mfma_f32_16x16x32_bf16 v[10:13], v[172:175], v[198:201], v[10:13]
	v_mfma_f32_16x16x32_bf16 v[6:9], v[164:167], v[214:217], v[6:9]
	v_mfma_f32_16x16x32_bf16 v[2:5], v[172:175], v[214:217], v[2:5]
	v_lshl_add_u64 v[222:223], v[228:229], 0, s[60:61]
	s_mov_b32 m0, s63
	s_nop 0
	global_load_lds_dwordx4 v[222:223], off
	v_mfma_f32_16x16x32_bf16 v[48:51], v[168:171], v[184:187], v[48:51]
	v_mfma_f32_16x16x32_bf16 v[44:47], v[176:179], v[184:187], v[44:47]
	v_mfma_f32_16x16x32_bf16 v[32:35], v[168:171], v[192:195], v[32:35]
	v_mfma_f32_16x16x32_bf16 v[28:31], v[176:179], v[192:195], v[28:31]
	v_mfma_f32_16x16x32_bf16 v[14:17], v[168:171], v[210:213], v[14:17]
	v_mfma_f32_16x16x32_bf16 v[10:13], v[176:179], v[210:213], v[10:13]
	v_mfma_f32_16x16x32_bf16 v[6:9], v[168:171], v[218:221], v[6:9]
	v_mfma_f32_16x16x32_bf16 v[2:5], v[176:179], v[218:221], v[2:5]
	s_setprio 0
	s_barrier
	s_add_i32 s75, s75, 2
	s_add_u32 s73, s73, 0x100
	s_addc_u32 s74, s74, 0
	s_add_u32 s40, s40, 0x100
	s_addc_u32 s41, s41, 0
	s_cmp_gt_u32 s75, 29
	s_cbranch_scc0 .LBB0_2634
	s_and_b64 vcc, exec, s[16:17]
	s_cbranch_vccz .LBB0_2637
	s_barrier
